# phase 3: half of the workgroups run the GLA state scan before their attention units and half after (on top of the phase-2 alternation)
# baseline (speedup 1.0000x reference)
.LBB0_88:
	s_and_b64 vcc, exec, s[0:1]
	s_cbranch_vccz .LBB0_130
	v_readlane_b32 s32, v249, 25
	s_nop 0
	s_bfe_u32 s32, s32, 0x10006
	s_cmp_eq_u32 s32, 1
	s_cbranch_scc1 .Lscan_late
.Lattn_start:
	v_readlane_b32 s0, v254, 36
	v_readlane_b32 s1, v254, 37
	s_lshl_b32 s0, s0, 6
	s_ashr_i32 s1, s0, 31
	v_readlane_b32 s4, v249, 56
	s_lshl_b64 s[0:1], s[0:1], 2
	v_readlane_b32 s16, v250, 4
	s_mov_b64 s[30:31], s[60:61]
	s_mov_b32 s23, s57
	s_mov_b64 s[24:25], s[62:63]
	v_readlane_b32 s17, v250, 5
	s_add_u32 s2, s16, s0
	v_readlane_b32 s48, v249, 38
	s_addc_u32 s3, s17, s1
	v_readlane_b32 s50, v249, 40
	v_readlane_b32 s5, v249, 57
	v_readlane_b32 s51, v249, 41
	s_add_u32 s4, s50, s0
	v_readlane_b32 s6, v249, 58
	v_readlane_b32 s18, v250, 6
	s_addc_u32 s5, s51, s1
	v_readlane_b32 s7, v249, 59
	v_readlane_b32 s19, v250, 7
	s_add_u32 s6, s18, s0
	v_readlane_b32 s8, v249, 60
	s_addc_u32 s7, s19, s1
	v_readlane_b32 s9, v249, 61
	v_readlane_b32 s49, v249, 39
	s_add_u32 s8, s48, s0
	v_mov_b32_e32 v0, v216
	s_addc_u32 s9, s49, s1
	s_mov_b64 s[0:1], 0
	v_mov_b32_e32 v3, 0
	s_waitcnt lgkmcnt(0)
	v_mov_b32_e32 v2, 0
	v_readlane_b32 s10, v249, 62
	v_readlane_b32 s11, v249, 63
	v_readlane_b32 s12, v250, 0
	v_readlane_b32 s13, v250, 1
	v_readlane_b32 s14, v250, 2
	v_readlane_b32 s15, v250, 3
	v_readlane_b32 s52, v249, 42
	v_readlane_b32 s53, v249, 43
	v_readlane_b32 s54, v249, 44
	v_readlane_b32 s55, v249, 45
	v_readlane_b32 s56, v249, 46
	v_readlane_b32 s57, v249, 47
	v_readlane_b32 s58, v249, 48
	v_readlane_b32 s59, v249, 49
	v_readlane_b32 s60, v249, 50
	v_readlane_b32 s61, v249, 51
	v_readlane_b32 s62, v249, 52
	v_readlane_b32 s63, v249, 53

.Lattn_exit:
	s_cmp_eq_u32 s32, 2
	s_cbranch_scc1 .LBB0_130

.LBB0_94:
	s_or_b64 exec, exec, s[0:1]
	s_cmp_eq_u32 s32, 1
	s_cbranch_scc0 .Lscan_ret_no
	s_mov_b32 s32, 2
	s_branch .Lattn_start
.Lscan_ret_no:
.LBB0_130:
	s_mov_b64 s[0:1], 0
